# hand-written pool phase: wave-per-item, scalar control flow, 23 row loads in flight
# speedup vs baseline: 1.0026x; 1.0026x over previous
; #define GAS __attribute__((address_space(1)))
; __device__ __forceinline__ void pool_phase(Frame& F) {
;     const int total = (MT / 8) * 64;
;     for (int i = blockIdx.x * 512 + F.tid; i < total; i += F.G * 512) {
;         const int r0 = (i >> 6) * 8, c = (i & 63) * 4, g = c >> 6; const bool smp = r0 >= TP; const int rr = smp ? r0 - TP : r0; const int b = smp ? rr >> 3 : rr >> 11, t0 = smp ? 0 : rr & 2047;
;         const bf16* ub = F.U + (size_t)(r0 - t0) * 256 + c;
;         f32x4 x[23];
; #pragma unroll
;         for (int k = 0; k < 23; ++k) { const int tau = t0 - 15 + k;
;             if (tau >= 0) { const u32x2v hb = *(const GAS u32x2v*)(ub + (size_t)tau * 256);
;                 x[k] = (f32x4){__builtin_bit_cast(float, hb.x << 16), __builtin_bit_cast(float, hb.x & 0xffff0000u), __builtin_bit_cast(float, hb.y << 16), __builtin_bit_cast(float, hb.y & 0xffff0000u)}; } else if (smp) x[k] = *(const GAS f32x4*)(F.state_pool + ((size_t)b * 15 + 15 + tau) * 256 + c); else x[k] = (f32x4){0.f, 0.f, 0.f, 0.f}; }
.LBB0_390:
	s_cmp_lt_i32 s70, 3
	s_cselect_b64 s[2:3], -1, 0
	s_add_u32 s38, s68, 0x5300000
	s_addc_u32 s39, s69, 0
	s_and_b64 s[6:7], s[2:3], s[0:1]
	s_andn2_b64 vcc, exec, s[6:7]
	s_cbranch_vccnz .LBB0_579
	s_mov_b32 s28, s88
	v_readfirstlane_b32 s40, v0
	v_readlane_b32 s48, v254, 9
	v_readlane_b32 s49, v254, 10
	v_readlane_b32 s50, v254, 58
	v_readlane_b32 s51, v254, 59
	s_nop 4
	s_lshr_b32 s40, s40, 6
	s_lshl_b32 s41, s88, 3
	s_add_i32 s40, s40, s41
	s_lshl_b32 s41, s79, 3
	s_add_u32 s44, s68, 0x7500000
	s_addc_u32 s45, s69, 0
	s_sub_u32 s44, s44, 0x1e00
	s_subb_u32 s45, s45, 0
	s_add_u32 s46, s68, 0x5300000
	s_addc_u32 s47, s69, 0
	s_mov_b32 s54, 0xffff0000
	s_mov_b32 s55, -1
	s_mov_b32 s56, 0
	s_mov_b32 s57, -1
	s_mov_b32 s58, 0
	s_mov_b32 s59, 0xffff0000
	v_lshlrev_b32_e32 v244, 3, v202
	v_lshlrev_b32_e32 v245, 4, v202
	v_lshrrev_b32_e32 v247, 4, v202
	v_lshlrev_b32_e64 v246, v247, 2
	v_cvt_f32_u32_e32 v246, v246
.Lpool_loop:
	s_cmp_ge_u32 s40, 0x880
	s_cbranch_scc1 .Lpool_done
	s_lshl_b32 s42, s40, 3
	s_cmp_ge_u32 s40, 0x800
	s_cbranch_scc1 .Lpool_smp
	s_and_b32 s43, s40, 0xff
	s_lshl_b32 s43, s43, 3
	s_lshl_b32 s32, s42, 9
	s_add_u32 s60, s44, s32
	s_addc_u32 s61, s45, 0
	s_add_u32 s62, s60, 0x1000
	s_addc_u32 s63, s61, 0
	s_add_u32 s30, s60, 0x2000
	s_addc_u32 s31, s61, 0
	global_load_dwordx2 v[6:7], v244, s[60:61]
	global_load_dwordx2 v[10:11], v244, s[60:61] offset:512
	global_load_dwordx2 v[14:15], v244, s[60:61] offset:1024
	global_load_dwordx2 v[18:19], v244, s[60:61] offset:1536
	global_load_dwordx2 v[22:23], v244, s[60:61] offset:2048
	global_load_dwordx2 v[26:27], v244, s[60:61] offset:2560
	global_load_dwordx2 v[30:31], v244, s[60:61] offset:3072
	global_load_dwordx2 v[34:35], v244, s[60:61] offset:3584
	global_load_dwordx2 v[38:39], v244, s[62:63]
	global_load_dwordx2 v[42:43], v244, s[62:63] offset:512
	global_load_dwordx2 v[46:47], v244, s[62:63] offset:1024
	global_load_dwordx2 v[50:51], v244, s[62:63] offset:1536
	global_load_dwordx2 v[54:55], v244, s[62:63] offset:2048
	global_load_dwordx2 v[58:59], v244, s[62:63] offset:2560
	global_load_dwordx2 v[62:63], v244, s[62:63] offset:3072
	global_load_dwordx2 v[66:67], v244, s[62:63] offset:3584
	global_load_dwordx2 v[70:71], v244, s[30:31]
	global_load_dwordx2 v[74:75], v244, s[30:31] offset:512
	global_load_dwordx2 v[78:79], v244, s[30:31] offset:1024
	global_load_dwordx2 v[82:83], v244, s[30:31] offset:1536
	global_load_dwordx2 v[86:87], v244, s[30:31] offset:2048
	global_load_dwordx2 v[90:91], v244, s[30:31] offset:2560
	global_load_dwordx2 v[94:95], v244, s[30:31] offset:3072
	s_waitcnt vmcnt(0)
	v_lshlrev_b32_e32 v4, 16, v6
	v_and_b32_e32 v5, s59, v6
	v_lshlrev_b32_e32 v6, 16, v7
	v_and_b32_e32 v7, s59, v7
	v_lshlrev_b32_e32 v8, 16, v10
	v_and_b32_e32 v9, s59, v10
	v_lshlrev_b32_e32 v10, 16, v11
	v_and_b32_e32 v11, s59, v11
	v_lshlrev_b32_e32 v12, 16, v14
	v_and_b32_e32 v13, s59, v14
	v_lshlrev_b32_e32 v14, 16, v15
	v_and_b32_e32 v15, s59, v15
	v_lshlrev_b32_e32 v16, 16, v18
	v_and_b32_e32 v17, s59, v18
	v_lshlrev_b32_e32 v18, 16, v19
	v_and_b32_e32 v19, s59, v19
	v_lshlrev_b32_e32 v20, 16, v22
	v_and_b32_e32 v21, s59, v22
	v_lshlrev_b32_e32 v22, 16, v23
	v_and_b32_e32 v23, s59, v23
	v_lshlrev_b32_e32 v24, 16, v26
	v_and_b32_e32 v25, s59, v26
	v_lshlrev_b32_e32 v26, 16, v27
	v_and_b32_e32 v27, s59, v27
	v_lshlrev_b32_e32 v28, 16, v30
	v_and_b32_e32 v29, s59, v30
	v_lshlrev_b32_e32 v30, 16, v31
	v_and_b32_e32 v31, s59, v31
	v_lshlrev_b32_e32 v32, 16, v34
	v_and_b32_e32 v33, s59, v34
	v_lshlrev_b32_e32 v34, 16, v35
	v_and_b32_e32 v35, s59, v35
	v_lshlrev_b32_e32 v36, 16, v38
	v_and_b32_e32 v37, s59, v38
	v_lshlrev_b32_e32 v38, 16, v39
	v_and_b32_e32 v39, s59, v39
	v_lshlrev_b32_e32 v40, 16, v42
	v_and_b32_e32 v41, s59, v42
	v_lshlrev_b32_e32 v42, 16, v43
	v_and_b32_e32 v43, s59, v43
	v_lshlrev_b32_e32 v44, 16, v46
	v_and_b32_e32 v45, s59, v46
	v_lshlrev_b32_e32 v46, 16, v47
	v_and_b32_e32 v47, s59, v47
	v_lshlrev_b32_e32 v48, 16, v50
	v_and_b32_e32 v49, s59, v50
	v_lshlrev_b32_e32 v50, 16, v51
	v_and_b32_e32 v51, s59, v51
	v_lshlrev_b32_e32 v52, 16, v54
	v_and_b32_e32 v53, s59, v54
	v_lshlrev_b32_e32 v54, 16, v55
	v_and_b32_e32 v55, s59, v55
	v_lshlrev_b32_e32 v56, 16, v58
	v_and_b32_e32 v57, s59, v58
	v_lshlrev_b32_e32 v58, 16, v59
	v_and_b32_e32 v59, s59, v59
	v_lshlrev_b32_e32 v60, 16, v62
	v_and_b32_e32 v61, s59, v62
	v_lshlrev_b32_e32 v62, 16, v63
	v_and_b32_e32 v63, s59, v63
	s_cmp_ge_u32 s43, 16
	s_cbranch_scc1 .Lpool_common
	v_mov_b32_e32 v4, 0
	v_mov_b32_e32 v5, 0
	v_mov_b32_e32 v6, 0
	v_mov_b32_e32 v7, 0
	v_mov_b32_e32 v8, 0
	v_mov_b32_e32 v9, 0
	v_mov_b32_e32 v10, 0
	v_mov_b32_e32 v11, 0
	v_mov_b32_e32 v12, 0
	v_mov_b32_e32 v13, 0
	v_mov_b32_e32 v14, 0
	v_mov_b32_e32 v15, 0
	v_mov_b32_e32 v16, 0
	v_mov_b32_e32 v17, 0
	v_mov_b32_e32 v18, 0
	v_mov_b32_e32 v19, 0
	v_mov_b32_e32 v20, 0
	v_mov_b32_e32 v21, 0
	v_mov_b32_e32 v22, 0
	v_mov_b32_e32 v23, 0
	v_mov_b32_e32 v24, 0
	v_mov_b32_e32 v25, 0
	v_mov_b32_e32 v26, 0
	v_mov_b32_e32 v27, 0
	v_mov_b32_e32 v28, 0
	v_mov_b32_e32 v29, 0
	v_mov_b32_e32 v30, 0
	v_mov_b32_e32 v31, 0
	s_cmp_eq_u32 s43, 8
	s_cbranch_scc1 .Lpool_common
	v_mov_b32_e32 v32, 0
	v_mov_b32_e32 v33, 0
	v_mov_b32_e32 v34, 0
	v_mov_b32_e32 v35, 0
	v_mov_b32_e32 v36, 0
	v_mov_b32_e32 v37, 0
	v_mov_b32_e32 v38, 0
	v_mov_b32_e32 v39, 0
	v_mov_b32_e32 v40, 0
	v_mov_b32_e32 v41, 0
	v_mov_b32_e32 v42, 0
	v_mov_b32_e32 v43, 0
	v_mov_b32_e32 v44, 0
	v_mov_b32_e32 v45, 0
	v_mov_b32_e32 v46, 0
	v_mov_b32_e32 v47, 0
	v_mov_b32_e32 v48, 0
	v_mov_b32_e32 v49, 0
	v_mov_b32_e32 v50, 0
	v_mov_b32_e32 v51, 0
	v_mov_b32_e32 v52, 0
	v_mov_b32_e32 v53, 0
	v_mov_b32_e32 v54, 0
	v_mov_b32_e32 v55, 0
	v_mov_b32_e32 v56, 0
	v_mov_b32_e32 v57, 0
	v_mov_b32_e32 v58, 0
	v_mov_b32_e32 v59, 0
	v_mov_b32_e32 v60, 0
	v_mov_b32_e32 v61, 0
	v_mov_b32_e32 v62, 0
	v_mov_b32_e32 v63, 0
	s_branch .Lpool_common
; #define GAS __attribute__((address_space(1)))
; __device__ __forceinline__ void pool_phase(Frame& F) {
;     ...
;         const bf16* ub = F.U + (size_t)(r0 - t0) * 256 + c;
;         f32x4 x[23];
; #pragma unroll
;         for (int k = 0; k < 23; ++k) { const int tau = t0 - 15 + k;
;             if (tau >= 0) { const u32x2v hb = *(const GAS u32x2v*)(ub + (size_t)tau * 256);
;                 x[k] = (f32x4){__builtin_bit_cast(float, hb.x << 16), __builtin_bit_cast(float, hb.x & 0xffff0000u), __builtin_bit_cast(float, hb.y << 16), __builtin_bit_cast(float, hb.y & 0xffff0000u)}; } else if (smp) x[k] = *(const GAS f32x4*)(F.state_pool + ((size_t)b * 15 + 15 + tau) * 256 + c); else x[k] = (f32x4){0.f, 0.f, 0.f, 0.f}; }
;         f32x4 s2[23], s4[23], s8[23], s16[8];
; #pragma unroll
;         for (int k = 1; k < 23; ++k) s2[k] = x[k] + x[k - 1];
; #pragma unroll
;         for (int k = 3; k < 23; ++k) s4[k] = s2[k] + s2[k - 2];
; #pragma unroll
;         for (int k = 7; k < 23; ++k) s8[k] = s4[k] + s4[k - 4];
; #pragma unroll
;         for (int k = 0; k < 8; ++k) s16[k] = s8[15 + k] + s8[7 + k];
;         const float wf = (float)(2 << g);
; #pragma unroll
;         for (int k = 0; k < 8; ++k) { const int t = t0 + k;
;             const f32x4 s = g == 0 ? s2[15 + k] : g == 1 ? s4[15 + k] : g == 2 ? s8[15 + k] : s16[k];
;             const float cnt = smp ? wf : fminf(wf, (float)(t + 1));
;             const f32x4 dd = s * (1.f / cnt) - x[15 + k];
.Lpool_smp:
	s_sub_u32 s32, s40, 0x800
	s_mul_i32 s33, s32, 0x3c00
	s_add_u32 s60, s48, s33
	s_addc_u32 s61, s49, 0
	s_add_u32 s62, s60, 0x1000
	s_addc_u32 s63, s61, 0
	s_add_u32 s30, s60, 0x2000
	s_addc_u32 s31, s61, 0
	s_add_u32 s34, s60, 0x3000
	s_addc_u32 s35, s61, 0
	global_load_dwordx4 v[4:7], v245, s[60:61]
	global_load_dwordx4 v[8:11], v245, s[60:61] offset:1024
	global_load_dwordx4 v[12:15], v245, s[60:61] offset:2048
	global_load_dwordx4 v[16:19], v245, s[60:61] offset:3072
	global_load_dwordx4 v[20:23], v245, s[62:63]
	global_load_dwordx4 v[24:27], v245, s[62:63] offset:1024
	global_load_dwordx4 v[28:31], v245, s[62:63] offset:2048
	global_load_dwordx4 v[32:35], v245, s[62:63] offset:3072
	global_load_dwordx4 v[36:39], v245, s[30:31]
	global_load_dwordx4 v[40:43], v245, s[30:31] offset:1024
	global_load_dwordx4 v[44:47], v245, s[30:31] offset:2048
	global_load_dwordx4 v[48:51], v245, s[30:31] offset:3072
	global_load_dwordx4 v[52:55], v245, s[34:35]
	global_load_dwordx4 v[56:59], v245, s[34:35] offset:1024
	global_load_dwordx4 v[60:63], v245, s[34:35] offset:2048
	s_lshl_b32 s32, s42, 9
	s_add_u32 s32, s32, 0x1e00
	s_add_u32 s32, s44, s32
	s_addc_u32 s33, s45, 0
	global_load_dwordx2 v[66:67], v244, s[32:33]
	global_load_dwordx2 v[70:71], v244, s[32:33] offset:512
	global_load_dwordx2 v[74:75], v244, s[32:33] offset:1024
	global_load_dwordx2 v[78:79], v244, s[32:33] offset:1536
	global_load_dwordx2 v[82:83], v244, s[32:33] offset:2048
	global_load_dwordx2 v[86:87], v244, s[32:33] offset:2560
	global_load_dwordx2 v[90:91], v244, s[32:33] offset:3072
	global_load_dwordx2 v[94:95], v244, s[32:33] offset:3584
	s_mov_b32 s43, 64
	s_waitcnt vmcnt(0)
.Lpool_common:
	v_lshlrev_b32_e32 v64, 16, v66
	v_and_b32_e32 v65, s59, v66
	v_lshlrev_b32_e32 v66, 16, v67
	v_and_b32_e32 v67, s59, v67
	v_lshlrev_b32_e32 v68, 16, v70
	v_and_b32_e32 v69, s59, v70
	v_lshlrev_b32_e32 v70, 16, v71
	v_and_b32_e32 v71, s59, v71
	v_lshlrev_b32_e32 v72, 16, v74
	v_and_b32_e32 v73, s59, v74
	v_lshlrev_b32_e32 v74, 16, v75
	v_and_b32_e32 v75, s59, v75
	v_lshlrev_b32_e32 v76, 16, v78
	v_and_b32_e32 v77, s59, v78
	v_lshlrev_b32_e32 v78, 16, v79
	v_and_b32_e32 v79, s59, v79
	v_lshlrev_b32_e32 v80, 16, v82
	v_and_b32_e32 v81, s59, v82
	v_lshlrev_b32_e32 v82, 16, v83
	v_and_b32_e32 v83, s59, v83
	v_lshlrev_b32_e32 v84, 16, v86
	v_and_b32_e32 v85, s59, v86
	v_lshlrev_b32_e32 v86, 16, v87
	v_and_b32_e32 v87, s59, v87
	v_lshlrev_b32_e32 v88, 16, v90
	v_and_b32_e32 v89, s59, v90
	v_lshlrev_b32_e32 v90, 16, v91
	v_and_b32_e32 v91, s59, v91
	v_lshlrev_b32_e32 v92, 16, v94
	v_and_b32_e32 v93, s59, v94
	v_lshlrev_b32_e32 v94, 16, v95
	v_and_b32_e32 v95, s59, v95
	s_add_i32 s32, s43, 1
	v_cvt_f32_u32_e32 v247, s32
	v_min_f32_e32 v247, v247, v246
	v_rcp_f32_e32 v236, v247
	s_add_i32 s32, s43, 2
	v_cvt_f32_u32_e32 v247, s32
	v_min_f32_e32 v247, v247, v246
	v_rcp_f32_e32 v237, v247
	s_add_i32 s32, s43, 3
	v_cvt_f32_u32_e32 v247, s32
	v_min_f32_e32 v247, v247, v246
	v_rcp_f32_e32 v238, v247
	s_add_i32 s32, s43, 4
	v_cvt_f32_u32_e32 v247, s32
	v_min_f32_e32 v247, v247, v246
	v_rcp_f32_e32 v239, v247
	s_add_i32 s32, s43, 5
	v_cvt_f32_u32_e32 v247, s32
	v_min_f32_e32 v247, v247, v246
	v_rcp_f32_e32 v240, v247
	s_add_i32 s32, s43, 6
	v_cvt_f32_u32_e32 v247, s32
	v_min_f32_e32 v247, v247, v246
	v_rcp_f32_e32 v241, v247
	s_add_i32 s32, s43, 7
	v_cvt_f32_u32_e32 v247, s32
	v_min_f32_e32 v247, v247, v246
	v_rcp_f32_e32 v242, v247
	s_add_i32 s32, s43, 8
	v_cvt_f32_u32_e32 v247, s32
	v_min_f32_e32 v247, v247, v246
	v_rcp_f32_e32 v243, v247
	v_pk_add_f32 v[100:101], v[8:9], v[4:5]
	v_pk_add_f32 v[102:103], v[10:11], v[6:7]
	v_pk_add_f32 v[104:105], v[12:13], v[8:9]
	v_pk_add_f32 v[106:107], v[14:15], v[10:11]
	v_pk_add_f32 v[108:109], v[16:17], v[12:13]
	v_pk_add_f32 v[110:111], v[18:19], v[14:15]
	v_pk_add_f32 v[112:113], v[20:21], v[16:17]
	v_pk_add_f32 v[114:115], v[22:23], v[18:19]
	v_pk_add_f32 v[116:117], v[24:25], v[20:21]
	v_pk_add_f32 v[118:119], v[26:27], v[22:23]
	v_pk_add_f32 v[120:121], v[28:29], v[24:25]
	v_pk_add_f32 v[122:123], v[30:31], v[26:27]
	v_pk_add_f32 v[124:125], v[32:33], v[28:29]
	v_pk_add_f32 v[126:127], v[34:35], v[30:31]
	v_pk_add_f32 v[128:129], v[36:37], v[32:33]
	v_pk_add_f32 v[130:131], v[38:39], v[34:35]
	v_pk_add_f32 v[132:133], v[40:41], v[36:37]
	v_pk_add_f32 v[134:135], v[42:43], v[38:39]
	v_pk_add_f32 v[136:137], v[44:45], v[40:41]
	v_pk_add_f32 v[138:139], v[46:47], v[42:43]
	v_pk_add_f32 v[140:141], v[48:49], v[44:45]
	v_pk_add_f32 v[142:143], v[50:51], v[46:47]
	v_pk_add_f32 v[144:145], v[52:53], v[48:49]
	v_pk_add_f32 v[146:147], v[54:55], v[50:51]
	v_pk_add_f32 v[148:149], v[56:57], v[52:53]
	v_pk_add_f32 v[150:151], v[58:59], v[54:55]
	v_pk_add_f32 v[152:153], v[60:61], v[56:57]
	v_pk_add_f32 v[154:155], v[62:63], v[58:59]
	v_pk_add_f32 v[156:157], v[64:65], v[60:61]
	v_pk_add_f32 v[158:159], v[66:67], v[62:63]
	v_pk_add_f32 v[160:161], v[68:69], v[64:65]
	v_pk_add_f32 v[162:163], v[70:71], v[66:67]
	v_pk_add_f32 v[164:165], v[72:73], v[68:69]
	v_pk_add_f32 v[166:167], v[74:75], v[70:71]
	v_pk_add_f32 v[168:169], v[76:77], v[72:73]
	v_pk_add_f32 v[170:171], v[78:79], v[74:75]
	v_pk_add_f32 v[172:173], v[80:81], v[76:77]
	v_pk_add_f32 v[174:175], v[82:83], v[78:79]
	v_pk_add_f32 v[176:177], v[84:85], v[80:81]
	v_pk_add_f32 v[178:179], v[86:87], v[82:83]
	v_pk_add_f32 v[180:181], v[88:89], v[84:85]
	v_pk_add_f32 v[182:183], v[90:91], v[86:87]
	v_pk_add_f32 v[184:185], v[92:93], v[88:89]
	v_pk_add_f32 v[186:187], v[94:95], v[90:91]
	v_mov_b64_e32 v[204:205], v[156:157]
	v_mov_b64_e32 v[206:207], v[158:159]
	v_mov_b64_e32 v[208:209], v[160:161]
; __device__ __forceinline__ void pool_phase(Frame& F) {
;     ...
;         for (int k = 1; k < 23; ++k) s2[k] = x[k] + x[k - 1];
; #pragma unroll
;         for (int k = 3; k < 23; ++k) s4[k] = s2[k] + s2[k - 2];
; #pragma unroll
;         for (int k = 7; k < 23; ++k) s8[k] = s4[k] + s4[k - 4];
; #pragma unroll
;         for (int k = 0; k < 8; ++k) s16[k] = s8[15 + k] + s8[7 + k];
;         const float wf = (float)(2 << g);
; #pragma unroll
;         for (int k = 0; k < 8; ++k) { const int t = t0 + k;
;             const f32x4 s = g == 0 ? s2[15 + k] : g == 1 ? s4[15 + k] : g == 2 ? s8[15 + k] : s16[k];
	v_mov_b64_e32 v[210:211], v[162:163]
	v_mov_b64_e32 v[212:213], v[164:165]
	v_mov_b64_e32 v[214:215], v[166:167]
	v_mov_b64_e32 v[216:217], v[168:169]
	v_mov_b64_e32 v[218:219], v[170:171]
	v_mov_b64_e32 v[220:221], v[172:173]
	v_mov_b64_e32 v[222:223], v[174:175]
	v_mov_b64_e32 v[224:225], v[176:177]
	v_mov_b64_e32 v[226:227], v[178:179]
	v_mov_b64_e32 v[228:229], v[180:181]
	v_mov_b64_e32 v[230:231], v[182:183]
	v_mov_b64_e32 v[232:233], v[184:185]
	v_mov_b64_e32 v[234:235], v[186:187]
	v_pk_add_f32 v[184:185], v[184:185], v[176:177]
	v_pk_add_f32 v[186:187], v[186:187], v[178:179]
	v_pk_add_f32 v[180:181], v[180:181], v[172:173]
	v_pk_add_f32 v[182:183], v[182:183], v[174:175]
	v_pk_add_f32 v[176:177], v[176:177], v[168:169]
	v_pk_add_f32 v[178:179], v[178:179], v[170:171]
	v_pk_add_f32 v[172:173], v[172:173], v[164:165]
	v_pk_add_f32 v[174:175], v[174:175], v[166:167]
	v_pk_add_f32 v[168:169], v[168:169], v[160:161]
	v_pk_add_f32 v[170:171], v[170:171], v[162:163]
	v_pk_add_f32 v[164:165], v[164:165], v[156:157]
	v_pk_add_f32 v[166:167], v[166:167], v[158:159]
	v_pk_add_f32 v[160:161], v[160:161], v[152:153]
	v_pk_add_f32 v[162:163], v[162:163], v[154:155]
	v_pk_add_f32 v[156:157], v[156:157], v[148:149]
	v_pk_add_f32 v[158:159], v[158:159], v[150:151]
	v_pk_add_f32 v[152:153], v[152:153], v[144:145]
	v_pk_add_f32 v[154:155], v[154:155], v[146:147]
	v_pk_add_f32 v[148:149], v[148:149], v[140:141]
	v_pk_add_f32 v[150:151], v[150:151], v[142:143]
	v_pk_add_f32 v[144:145], v[144:145], v[136:137]
	v_pk_add_f32 v[146:147], v[146:147], v[138:139]
	v_pk_add_f32 v[140:141], v[140:141], v[132:133]
	v_pk_add_f32 v[142:143], v[142:143], v[134:135]
	v_pk_add_f32 v[136:137], v[136:137], v[128:129]
	v_pk_add_f32 v[138:139], v[138:139], v[130:131]
	v_pk_add_f32 v[132:133], v[132:133], v[124:125]
	v_pk_add_f32 v[134:135], v[134:135], v[126:127]
	v_pk_add_f32 v[128:129], v[128:129], v[120:121]
	v_pk_add_f32 v[130:131], v[130:131], v[122:123]
	v_pk_add_f32 v[124:125], v[124:125], v[116:117]
	v_pk_add_f32 v[126:127], v[126:127], v[118:119]
	v_pk_add_f32 v[120:121], v[120:121], v[112:113]
	v_pk_add_f32 v[122:123], v[122:123], v[114:115]
	v_pk_add_f32 v[116:117], v[116:117], v[108:109]
	v_pk_add_f32 v[118:119], v[118:119], v[110:111]
	v_pk_add_f32 v[112:113], v[112:113], v[104:105]
	v_pk_add_f32 v[114:115], v[114:115], v[106:107]
	v_pk_add_f32 v[108:109], v[108:109], v[100:101]
	v_pk_add_f32 v[110:111], v[110:111], v[102:103]
	v_cndmask_b32_e64 v204, v204, v156, s[54:55]
	v_cndmask_b32_e64 v205, v205, v157, s[54:55]
	v_cndmask_b32_e64 v206, v206, v158, s[54:55]
	v_cndmask_b32_e64 v207, v207, v159, s[54:55]
	v_cndmask_b32_e64 v208, v208, v160, s[54:55]
	v_cndmask_b32_e64 v209, v209, v161, s[54:55]
	v_cndmask_b32_e64 v210, v210, v162, s[54:55]
	v_cndmask_b32_e64 v211, v211, v163, s[54:55]
	v_cndmask_b32_e64 v212, v212, v164, s[54:55]
	v_cndmask_b32_e64 v213, v213, v165, s[54:55]
	v_cndmask_b32_e64 v214, v214, v166, s[54:55]
	v_cndmask_b32_e64 v215, v215, v167, s[54:55]
	v_cndmask_b32_e64 v216, v216, v168, s[54:55]
	v_cndmask_b32_e64 v217, v217, v169, s[54:55]
	v_cndmask_b32_e64 v218, v218, v170, s[54:55]
	v_cndmask_b32_e64 v219, v219, v171, s[54:55]
	v_cndmask_b32_e64 v220, v220, v172, s[54:55]
	v_cndmask_b32_e64 v221, v221, v173, s[54:55]
	v_cndmask_b32_e64 v222, v222, v174, s[54:55]
	v_cndmask_b32_e64 v223, v223, v175, s[54:55]
	v_cndmask_b32_e64 v224, v224, v176, s[54:55]
	v_cndmask_b32_e64 v225, v225, v177, s[54:55]
	v_cndmask_b32_e64 v226, v226, v178, s[54:55]
	v_cndmask_b32_e64 v227, v227, v179, s[54:55]
	v_cndmask_b32_e64 v228, v228, v180, s[54:55]
	v_cndmask_b32_e64 v229, v229, v181, s[54:55]
	v_cndmask_b32_e64 v230, v230, v182, s[54:55]
	v_cndmask_b32_e64 v231, v231, v183, s[54:55]
	v_cndmask_b32_e64 v232, v232, v184, s[54:55]
	v_cndmask_b32_e64 v233, v233, v185, s[54:55]
	v_cndmask_b32_e64 v234, v234, v186, s[54:55]
	v_cndmask_b32_e64 v235, v235, v187, s[54:55]
	v_pk_add_f32 v[184:185], v[184:185], v[168:169]
	v_pk_add_f32 v[186:187], v[186:187], v[170:171]
	v_pk_add_f32 v[180:181], v[180:181], v[164:165]
	v_pk_add_f32 v[182:183], v[182:183], v[166:167]
	v_pk_add_f32 v[176:177], v[176:177], v[160:161]
	v_pk_add_f32 v[178:179], v[178:179], v[162:163]
	v_pk_add_f32 v[172:173], v[172:173], v[156:157]
	v_pk_add_f32 v[174:175], v[174:175], v[158:159]
	v_pk_add_f32 v[168:169], v[168:169], v[152:153]
	v_pk_add_f32 v[170:171], v[170:171], v[154:155]
	v_pk_add_f32 v[164:165], v[164:165], v[148:149]
	v_pk_add_f32 v[166:167], v[166:167], v[150:151]
	v_pk_add_f32 v[160:161], v[160:161], v[144:145]
	v_pk_add_f32 v[162:163], v[162:163], v[146:147]
	v_pk_add_f32 v[156:157], v[156:157], v[140:141]
	v_pk_add_f32 v[158:159], v[158:159], v[142:143]
	v_pk_add_f32 v[152:153], v[152:153], v[136:137]
	v_pk_add_f32 v[154:155], v[154:155], v[138:139]
	v_pk_add_f32 v[148:149], v[148:149], v[132:133]
	v_pk_add_f32 v[150:151], v[150:151], v[134:135]
	v_pk_add_f32 v[144:145], v[144:145], v[128:129]
	v_pk_add_f32 v[146:147], v[146:147], v[130:131]
	v_pk_add_f32 v[140:141], v[140:141], v[124:125]
	v_pk_add_f32 v[142:143], v[142:143], v[126:127]
	v_pk_add_f32 v[136:137], v[136:137], v[120:121]
	v_pk_add_f32 v[138:139], v[138:139], v[122:123]
	v_pk_add_f32 v[132:133], v[132:133], v[116:117]
	v_pk_add_f32 v[134:135], v[134:135], v[118:119]
	v_pk_add_f32 v[128:129], v[128:129], v[112:113]
	v_pk_add_f32 v[130:131], v[130:131], v[114:115]
	v_pk_add_f32 v[124:125], v[124:125], v[108:109]
	v_pk_add_f32 v[126:127], v[126:127], v[110:111]
	v_cndmask_b32_e64 v204, v204, v156, s[56:57]
	v_cndmask_b32_e64 v205, v205, v157, s[56:57]
	v_cndmask_b32_e64 v206, v206, v158, s[56:57]
; #define GAS __attribute__((address_space(1)))
; __device__ __forceinline__ unsigned pk2(float lo, float hi) { const pkf2_t v = {lo, hi}; const pkb2_t b = __builtin_convertvector(v, pkb2_t); return __builtin_bit_cast(unsigned, b); }
; __device__ __forceinline__ void pool_phase(Frame& F) {
;     ...
;         for (int k = 7; k < 23; ++k) s8[k] = s4[k] + s4[k - 4];
; #pragma unroll
;         for (int k = 0; k < 8; ++k) s16[k] = s8[15 + k] + s8[7 + k];
;         const float wf = (float)(2 << g);
; #pragma unroll
;         for (int k = 0; k < 8; ++k) { const int t = t0 + k;
;             const f32x4 s = g == 0 ? s2[15 + k] : g == 1 ? s4[15 + k] : g == 2 ? s8[15 + k] : s16[k];
;             const float cnt = smp ? wf : fminf(wf, (float)(t + 1));
;             const f32x4 dd = s * (1.f / cnt) - x[15 + k];
;             *(GAS u32x2v*)(F.MIX + (size_t)(r0 + k) * D + c) = (u32x2v){pk2(dd[0], dd[1]), pk2(dd[2], dd[3])}; }
;         if (smp || t0 == 2040) { float* np = (smp ? F.o_pool_s : F.o_pool_p) + (size_t)b * 15 * 256 + c;
; #pragma unroll
;             for (int k = 0; k < 15; ++k) *(GAS f32x4*)(np + k * 256) = x[8 + k]; }
	v_cndmask_b32_e64 v207, v207, v159, s[56:57]
	v_cndmask_b32_e64 v208, v208, v160, s[56:57]
	v_cndmask_b32_e64 v209, v209, v161, s[56:57]
	v_cndmask_b32_e64 v210, v210, v162, s[56:57]
	v_cndmask_b32_e64 v211, v211, v163, s[56:57]
	v_cndmask_b32_e64 v212, v212, v164, s[56:57]
	v_cndmask_b32_e64 v213, v213, v165, s[56:57]
	v_cndmask_b32_e64 v214, v214, v166, s[56:57]
	v_cndmask_b32_e64 v215, v215, v167, s[56:57]
	v_cndmask_b32_e64 v216, v216, v168, s[56:57]
	v_cndmask_b32_e64 v217, v217, v169, s[56:57]
	v_cndmask_b32_e64 v218, v218, v170, s[56:57]
	v_cndmask_b32_e64 v219, v219, v171, s[56:57]
	v_cndmask_b32_e64 v220, v220, v172, s[56:57]
	v_cndmask_b32_e64 v221, v221, v173, s[56:57]
	v_cndmask_b32_e64 v222, v222, v174, s[56:57]
	v_cndmask_b32_e64 v223, v223, v175, s[56:57]
	v_cndmask_b32_e64 v224, v224, v176, s[56:57]
	v_cndmask_b32_e64 v225, v225, v177, s[56:57]
	v_cndmask_b32_e64 v226, v226, v178, s[56:57]
	v_cndmask_b32_e64 v227, v227, v179, s[56:57]
	v_cndmask_b32_e64 v228, v228, v180, s[56:57]
	v_cndmask_b32_e64 v229, v229, v181, s[56:57]
	v_cndmask_b32_e64 v230, v230, v182, s[56:57]
	v_cndmask_b32_e64 v231, v231, v183, s[56:57]
	v_cndmask_b32_e64 v232, v232, v184, s[56:57]
	v_cndmask_b32_e64 v233, v233, v185, s[56:57]
	v_cndmask_b32_e64 v234, v234, v186, s[56:57]
	v_cndmask_b32_e64 v235, v235, v187, s[56:57]
	v_pk_add_f32 v[156:157], v[156:157], v[124:125]
	v_pk_add_f32 v[158:159], v[158:159], v[126:127]
	v_pk_add_f32 v[160:161], v[160:161], v[128:129]
	v_pk_add_f32 v[162:163], v[162:163], v[130:131]
	v_pk_add_f32 v[164:165], v[164:165], v[132:133]
	v_pk_add_f32 v[166:167], v[166:167], v[134:135]
	v_pk_add_f32 v[168:169], v[168:169], v[136:137]
	v_pk_add_f32 v[170:171], v[170:171], v[138:139]
	v_pk_add_f32 v[172:173], v[172:173], v[140:141]
	v_pk_add_f32 v[174:175], v[174:175], v[142:143]
	v_pk_add_f32 v[176:177], v[176:177], v[144:145]
	v_pk_add_f32 v[178:179], v[178:179], v[146:147]
	v_pk_add_f32 v[180:181], v[180:181], v[148:149]
	v_pk_add_f32 v[182:183], v[182:183], v[150:151]
	v_pk_add_f32 v[184:185], v[184:185], v[152:153]
	v_pk_add_f32 v[186:187], v[186:187], v[154:155]
	v_cndmask_b32_e64 v204, v204, v156, s[58:59]
	v_cndmask_b32_e64 v205, v205, v157, s[58:59]
	v_cndmask_b32_e64 v206, v206, v158, s[58:59]
	v_cndmask_b32_e64 v207, v207, v159, s[58:59]
	v_cndmask_b32_e64 v208, v208, v160, s[58:59]
	v_cndmask_b32_e64 v209, v209, v161, s[58:59]
	v_cndmask_b32_e64 v210, v210, v162, s[58:59]
	v_cndmask_b32_e64 v211, v211, v163, s[58:59]
	v_cndmask_b32_e64 v212, v212, v164, s[58:59]
	v_cndmask_b32_e64 v213, v213, v165, s[58:59]
	v_cndmask_b32_e64 v214, v214, v166, s[58:59]
	v_cndmask_b32_e64 v215, v215, v167, s[58:59]
	v_cndmask_b32_e64 v216, v216, v168, s[58:59]
	v_cndmask_b32_e64 v217, v217, v169, s[58:59]
	v_cndmask_b32_e64 v218, v218, v170, s[58:59]
	v_cndmask_b32_e64 v219, v219, v171, s[58:59]
	v_cndmask_b32_e64 v220, v220, v172, s[58:59]
	v_cndmask_b32_e64 v221, v221, v173, s[58:59]
	v_cndmask_b32_e64 v222, v222, v174, s[58:59]
	v_cndmask_b32_e64 v223, v223, v175, s[58:59]
	v_cndmask_b32_e64 v224, v224, v176, s[58:59]
	v_cndmask_b32_e64 v225, v225, v177, s[58:59]
	v_cndmask_b32_e64 v226, v226, v178, s[58:59]
	v_cndmask_b32_e64 v227, v227, v179, s[58:59]
	v_cndmask_b32_e64 v228, v228, v180, s[58:59]
	v_cndmask_b32_e64 v229, v229, v181, s[58:59]
	v_cndmask_b32_e64 v230, v230, v182, s[58:59]
	v_cndmask_b32_e64 v231, v231, v183, s[58:59]
	v_cndmask_b32_e64 v232, v232, v184, s[58:59]
	v_cndmask_b32_e64 v233, v233, v185, s[58:59]
	v_cndmask_b32_e64 v234, v234, v186, s[58:59]
	v_cndmask_b32_e64 v235, v235, v187, s[58:59]
	v_fma_f32 v204, v204, v236, -v64
	v_fma_f32 v205, v205, v236, -v65
	v_fma_f32 v206, v206, v236, -v66
	v_fma_f32 v207, v207, v236, -v67
	v_fma_f32 v208, v208, v237, -v68
	v_fma_f32 v209, v209, v237, -v69
	v_fma_f32 v210, v210, v237, -v70
	v_fma_f32 v211, v211, v237, -v71
	v_fma_f32 v212, v212, v238, -v72
	v_fma_f32 v213, v213, v238, -v73
	v_fma_f32 v214, v214, v238, -v74
	v_fma_f32 v215, v215, v238, -v75
	v_fma_f32 v216, v216, v239, -v76
	v_fma_f32 v217, v217, v239, -v77
	v_fma_f32 v218, v218, v239, -v78
	v_fma_f32 v219, v219, v239, -v79
	v_fma_f32 v220, v220, v240, -v80
	v_fma_f32 v221, v221, v240, -v81
	v_fma_f32 v222, v222, v240, -v82
	v_fma_f32 v223, v223, v240, -v83
	v_fma_f32 v224, v224, v241, -v84
	v_fma_f32 v225, v225, v241, -v85
	v_fma_f32 v226, v226, v241, -v86
	v_fma_f32 v227, v227, v241, -v87
	v_fma_f32 v228, v228, v242, -v88
	v_fma_f32 v229, v229, v242, -v89
	v_fma_f32 v230, v230, v242, -v90
	v_fma_f32 v231, v231, v242, -v91
	v_fma_f32 v232, v232, v243, -v92
	v_fma_f32 v233, v233, v243, -v93
	v_fma_f32 v234, v234, v243, -v94
	v_fma_f32 v235, v235, v243, -v95
	v_cvt_pk_bf16_f32 v100, v204, v205
	v_cvt_pk_bf16_f32 v101, v206, v207
	v_cvt_pk_bf16_f32 v104, v208, v209
	v_cvt_pk_bf16_f32 v105, v210, v211
	v_cvt_pk_bf16_f32 v108, v212, v213
	v_cvt_pk_bf16_f32 v109, v214, v215
	v_cvt_pk_bf16_f32 v112, v216, v217
	v_cvt_pk_bf16_f32 v113, v218, v219
	v_cvt_pk_bf16_f32 v116, v220, v221
	v_cvt_pk_bf16_f32 v117, v222, v223
	v_cvt_pk_bf16_f32 v120, v224, v225
	v_cvt_pk_bf16_f32 v121, v226, v227
	v_cvt_pk_bf16_f32 v124, v228, v229
	v_cvt_pk_bf16_f32 v125, v230, v231
	v_cvt_pk_bf16_f32 v128, v232, v233
	v_cvt_pk_bf16_f32 v129, v234, v235
	s_lshl_b32 s32, s42, 11
	s_add_u32 s60, s46, s32
	s_addc_u32 s61, s47, 0
	s_add_u32 s62, s60, 0x1000
	s_addc_u32 s63, s61, 0
	s_add_u32 s30, s60, 0x2000
	s_addc_u32 s31, s61, 0
	s_add_u32 s34, s60, 0x3000
	s_addc_u32 s35, s61, 0
	global_store_dwordx2 v244, v[100:101], s[60:61]
	global_store_dwordx2 v244, v[104:105], s[60:61] offset:2048
	global_store_dwordx2 v244, v[108:109], s[62:63]
	global_store_dwordx2 v244, v[112:113], s[62:63] offset:2048
	global_store_dwordx2 v244, v[116:117], s[30:31]
	global_store_dwordx2 v244, v[120:121], s[30:31] offset:2048
	global_store_dwordx2 v244, v[124:125], s[34:35]
	global_store_dwordx2 v244, v[128:129], s[34:35] offset:2048
	s_cmp_ge_u32 s40, 0x800
	s_cbranch_scc1 .Lpool_np_smp
	s_and_b32 s32, s40, 0xff
	s_cmp_lg_u32 s32, 0xff
	s_cbranch_scc1 .Lpool_next
	s_lshr_b32 s32, s40, 8
	s_mul_i32 s32, s32, 0x3c00
	s_add_u32 s32, s32, 0x4400000
	s_branch .Lpool_np
; #define GAS __attribute__((address_space(1)))
; #define LAS __attribute__((address_space(3)))
; __device__ __forceinline__ void pool_phase(Frame& F) {
;     ...
;         if (smp || t0 == 2040) { float* np = (smp ? F.o_pool_s : F.o_pool_p) + (size_t)b * 15 * 256 + c;
; #pragma unroll
;             for (int k = 0; k < 15; ++k) *(GAS f32x4*)(np + k * 256) = x[8 + k]; }
;     }
; }
; __device__ __forceinline__ void hgrn_passA(Frame& F, u32x2v* HU, float* HD) {
;     ...
;     const int tid = F.tid, c8 = tid & 15, tq = tid >> 4, w = F.wave, lane = F.lane, l15 = lane & 15, lq = lane >> 4;
;     for (int u = blockIdx.x; u < HG_NU; u += F.G) {
;         const int sc = u & 7, bh = u >> 3, b = bh >> 2, h = bh & 3;
;         const size_t rbase = (size_t)(b * 2048 + sc * 256 + tq * 8) * 512 + h * 128 + 8 * c8;
;         f32x4 lf[8][2]; v4u vq[8];
; #pragma unroll
;         for (int i = 0; i < 8; ++i) { typedef _Float16 h8_t __attribute__((ext_vector_type(8))); const h8_t hv = *(const GAS h8_t*)(F.LOGF + rbase + (size_t)i * 512);
;             lf[i][0] = (f32x4){(float)hv[0], (float)hv[1], (float)hv[2], (float)hv[3]}; lf[i][1] = (f32x4){(float)hv[4], (float)hv[5], (float)hv[6], (float)hv[7]};
;             }
; #pragma unroll
;         for (int i = 1; i < 8; ++i) { lf[i][0] += lf[i - 1][0]; lf[i][1] += lf[i - 1][1]; }
;         *(LAS f32x4*)(segtot + tq * 128 + 8 * c8) = lf[7][0]; *(LAS f32x4*)(segtot + tq * 128 + 8 * c8 + 4) = lf[7][1];
;         __syncthreads();
;         f32x4 off[2] = {(f32x4){0.f, 0.f, 0.f, 0.f}, (f32x4){0.f, 0.f, 0.f, 0.f}}, aend[2] = {(f32x4){0.f, 0.f, 0.f, 0.f}, (f32x4){0.f, 0.f, 0.f, 0.f}};
; #pragma unroll 8
;         for (int s2 = 0; s2 < 32; ++s2) { const f32x4 t0 = *(const LAS f32x4*)(segtot + s2 * 128 + 8 * c8), t1 = *(const LAS f32x4*)(segtot + s2 * 128 + 8 * c8 + 4);
;             aend[0] += t0; aend[1] += t1; if (s2 < tq) { off[0] += t0; off[1] += t1; } }
;         __syncthreads();
;         if (tq == 0) { f32x4 d0, d1;
; #pragma unroll
;             for (int e = 0; e < 4; ++e) { d0[e] = __expf(aend[0][e]); d1[e] = __expf(aend[1][e]); }
;             *(GAS f32x4*)(HD + (size_t)u * 128 + 8 * c8) = d0; *(GAS f32x4*)(HD + (size_t)u * 128 + 8 * c8 + 4) = d1; }
; #pragma unroll
;         for (int jh = 0; jh < 2; ++jh) {
;             unsigned ke[4][4];
; #pragma unroll
;             for (int i = 0; i < 8; ++i)
; #pragma unroll
.Lpool_np_smp:
	s_sub_u32 s32, s40, 0x800
	s_mul_i32 s32, s32, 0x3c00
	s_add_u32 s32, s32, 0x4a4a000
.Lpool_np:
	s_add_u32 s60, s50, s32
	s_addc_u32 s61, s51, 0
	s_add_u32 s62, s60, 0x1000
	s_addc_u32 s63, s61, 0
	s_add_u32 s30, s60, 0x2000
	s_addc_u32 s31, s61, 0
	s_add_u32 s34, s60, 0x3000
	s_addc_u32 s35, s61, 0
	global_store_dwordx4 v245, v[36:39], s[60:61]
	global_store_dwordx4 v245, v[40:43], s[60:61] offset:1024
	global_store_dwordx4 v245, v[44:47], s[60:61] offset:2048
	global_store_dwordx4 v245, v[48:51], s[60:61] offset:3072
	global_store_dwordx4 v245, v[52:55], s[62:63]
	global_store_dwordx4 v245, v[56:59], s[62:63] offset:1024
	global_store_dwordx4 v245, v[60:63], s[62:63] offset:2048
	global_store_dwordx4 v245, v[64:67], s[62:63] offset:3072
	global_store_dwordx4 v245, v[68:71], s[30:31]
	global_store_dwordx4 v245, v[72:75], s[30:31] offset:1024
	global_store_dwordx4 v245, v[76:79], s[30:31] offset:2048
	global_store_dwordx4 v245, v[80:83], s[30:31] offset:3072
	global_store_dwordx4 v245, v[84:87], s[34:35]
	global_store_dwordx4 v245, v[88:91], s[34:35] offset:1024
	global_store_dwordx4 v245, v[92:95], s[34:35] offset:2048
.Lpool_next:
	s_add_i32 s40, s40, s41
	s_branch .Lpool_loop
.Lpool_done:
	s_mov_b32 s88, s28
	s_cmpk_gt_i32 s28, 0xff
	s_cbranch_scc1 .LBB0_579
	v_lshlrev_b32_e32 v111, 3, v0
	s_waitcnt lgkmcnt(0)
	v_and_b32_e32 v54, 0x78, v111
	v_and_b32_e32 v110, 15, v0
	v_mov_b32_e32 v57, 0
	v_lshlrev_b32_e32 v56, 2, v54
	v_lshl_add_u64 v[2:3], s[68:69], 0, v[56:57]
	s_mov_b64 s[2:3], 0x5200000
	v_readlane_b32 s0, v254, 39
	v_or_b32_e32 v52, 0x70, v110
	v_lshl_add_u64 v[58:59], v[2:3], 0, s[2:3]
	v_lshl_or_b32 v2, s0, 4, v110
	v_lshlrev_b32_e32 v53, 9, v52
	v_lshrrev_b32_e32 v52, 3, v52
	v_lshrrev_b32_e32 v55, 4, v202
	v_add_u32_e32 v114, 0, v56
	v_lshrrev_b32_e32 v3, 3, v2
	v_lshlrev_b32_e32 v56, 3, v202
	v_bitop3_b32 v52, v52, v0, 15 bitop3:0x78
	v_xor_b32_e32 v4, v3, v0
	v_lshl_add_u32 v5, v2, 9, 0
	v_lshl_add_u64 v[2:3], s[68:69], 0, v[56:57]
	s_add_i32 s2, 0, 0x10000
	v_xor_b32_e32 v56, v52, v55
	v_bfe_u32 v31, v0, 3, 1
	v_or_b32_e32 v34, 16, v110
	v_lshl_add_u32 v62, v56, 4, s2
	v_or_b32_e32 v56, 4, v55
	v_bitop3_b32 v31, v31, v0, 15 bitop3:0x78
	v_lshlrev_b32_e32 v35, 9, v34
	v_lshrrev_b32_e32 v34, 3, v34
	v_or_b32_e32 v37, 32, v110
	v_bitop3_b32 v60, v4, v56, 15 bitop3:0x6c
	v_bitop3_b32 v34, v34, v0, 15 bitop3:0x78
	v_lshlrev_b32_e32 v38, 9, v37
	v_lshrrev_b32_e32 v37, 3, v37
	v_or_b32_e32 v40, 48, v110
	v_lshlrev_b32_e32 v63, 4, v60
	v_xor_b32_e32 v60, v31, v56
	v_bitop3_b32 v37, v37, v0, 15 bitop3:0x78
	v_lshlrev_b32_e32 v41, 9, v40
	v_lshrrev_b32_e32 v40, 3, v40
	v_or_b32_e32 v43, 64, v110
	v_lshl_add_u32 v64, v60, 4, s2
	v_xor_b32_e32 v60, v34, v56
	v_bitop3_b32 v40, v40, v0, 15 bitop3:0x78
	v_lshlrev_b32_e32 v44, 9, v43
	v_lshrrev_b32_e32 v43, 3, v43
	v_or_b32_e32 v46, 0x50, v110
	v_lshl_add_u32 v65, v60, 4, s2
	v_xor_b32_e32 v60, v37, v56
	v_bitop3_b32 v43, v43, v0, 15 bitop3:0x78
	v_lshlrev_b32_e32 v47, 9, v46
	v_lshrrev_b32_e32 v46, 3, v46
	v_or_b32_e32 v49, 0x60, v110
	v_lshl_add_u32 v66, v60, 4, s2
	v_xor_b32_e32 v60, v40, v56
	v_bitop3_b32 v46, v46, v0, 15 bitop3:0x78
	v_lshlrev_b32_e32 v50, 9, v49
	v_lshrrev_b32_e32 v49, 3, v49
	v_lshl_add_u32 v67, v60, 4, s2
	v_xor_b32_e32 v60, v43, v56
	v_bitop3_b32 v49, v49, v0, 15 bitop3:0x78
	v_lshl_add_u32 v68, v60, 4, s2
	v_xor_b32_e32 v60, v46, v56
	v_lshl_add_u32 v69, v60, 4, s2
	v_xor_b32_e32 v60, v49, v56
	v_xor_b32_e32 v56, v52, v56
	v_lshl_add_u32 v71, v56, 4, s2
	v_or_b32_e32 v56, 8, v55
	v_lshl_add_u32 v70, v60, 4, s2
	v_bitop3_b32 v60, v4, v56, 15 bitop3:0x6c
	v_lshlrev_b32_e32 v72, 4, v60
	v_xor_b32_e32 v60, v31, v56
	v_lshl_add_u32 v73, v60, 4, s2
	v_xor_b32_e32 v60, v34, v56
	v_lshl_add_u32 v74, v60, 4, s2
	v_xor_b32_e32 v60, v37, v56
	v_lshl_add_u32 v75, v60, 4, s2
	v_xor_b32_e32 v60, v40, v56
	v_lshl_add_u32 v76, v60, 4, s2
	v_xor_b32_e32 v60, v43, v56
	v_lshl_add_u32 v77, v60, 4, s2
	v_xor_b32_e32 v60, v46, v56
	v_lshl_add_u32 v78, v60, 4, s2
	v_xor_b32_e32 v60, v49, v56
	v_xor_b32_e32 v56, v52, v56
	v_lshl_add_u32 v80, v56, 4, s2
	v_or_b32_e32 v56, 12, v55
	v_lshl_add_u32 v79, v60, 4, s2
	v_bitop3_b32 v60, v4, v56, 15 bitop3:0x6c
	v_lshlrev_b32_e32 v81, 4, v60
	v_xor_b32_e32 v60, v31, v56
	v_lshl_add_u32 v82, v60, 4, s2
	v_xor_b32_e32 v60, v34, v56
	v_lshl_add_u32 v83, v60, 4, s2
	v_xor_b32_e32 v60, v37, v56
	v_lshl_add_u32 v84, v60, 4, s2
	v_xor_b32_e32 v60, v40, v56
	v_lshl_add_u32 v85, v60, 4, s2
	v_xor_b32_e32 v60, v43, v56
	v_lshl_add_u32 v86, v60, 4, s2
	v_xor_b32_e32 v60, v46, v56
	v_lshl_add_u32 v87, v60, 4, s2
	v_xor_b32_e32 v60, v49, v56
	v_xor_b32_e32 v56, v52, v56
	v_lshl_add_u32 v89, v56, 4, s2
	v_or_b32_e32 v56, 16, v55
	v_lshl_add_u32 v88, v60, 4, s2
	v_bitop3_b32 v60, v4, v56, 15 bitop3:0x6c
	v_lshlrev_b32_e32 v90, 4, v60
	v_xor_b32_e32 v60, v31, v56
	v_lshl_add_u32 v91, v60, 4, s2
	v_xor_b32_e32 v60, v34, v56
	v_lshl_add_u32 v92, v60, 4, s2
	v_xor_b32_e32 v60, v37, v56
	v_lshl_add_u32 v93, v60, 4, s2
	v_xor_b32_e32 v60, v40, v56
	v_lshl_add_u32 v94, v60, 4, s2
	v_xor_b32_e32 v60, v43, v56
	v_lshl_add_u32 v95, v60, 4, s2
	v_xor_b32_e32 v60, v46, v56
	v_lshl_add_u32 v96, v60, 4, s2
	v_xor_b32_e32 v60, v49, v56
	v_xor_b32_e32 v56, v52, v56
	v_lshl_add_u32 v98, v56, 4, s2
	v_or_b32_e32 v56, 20, v55
	v_lshl_add_u32 v97, v60, 4, s2
	v_bitop3_b32 v60, v4, v56, 15 bitop3:0x6c
	v_lshlrev_b32_e32 v99, 4, v60
	v_xor_b32_e32 v60, v31, v56
	v_lshl_add_u32 v100, v60, 4, s2
	v_xor_b32_e32 v60, v34, v56
	v_lshl_add_u32 v101, v60, 4, s2
	v_xor_b32_e32 v60, v37, v56
	v_lshl_add_u32 v102, v60, 4, s2
	v_xor_b32_e32 v60, v40, v56
	v_lshl_add_u32 v103, v60, 4, s2
	v_xor_b32_e32 v60, v43, v56
	v_lshl_add_u32 v104, v60, 4, s2
	v_xor_b32_e32 v60, v46, v56
	v_lshl_add_u32 v105, v60, 4, s2
	v_xor_b32_e32 v60, v49, v56
	v_xor_b32_e32 v56, v52, v56
	v_lshl_add_u32 v107, v56, 4, s2
	v_or_b32_e32 v56, 24, v55
	v_lshl_add_u32 v106, v60, 4, s2
	v_bitop3_b32 v60, v4, v56, 15 bitop3:0x6c
	v_lshlrev_b32_e32 v108, 4, v60
	v_xor_b32_e32 v60, v31, v56
	v_lshl_add_u32 v109, v60, 4, s2
	v_xor_b32_e32 v60, v34, v56
	v_lshl_add_u32 v187, v60, 4, s2
	v_xor_b32_e32 v60, v37, v56
	v_lshl_add_u32 v188, v60, 4, s2
	v_xor_b32_e32 v60, v40, v56
	v_lshl_add_u32 v189, v60, 4, s2
	v_xor_b32_e32 v60, v43, v56
	s_waitcnt vmcnt(0)
; #define GAS __attribute__((address_space(1)))
; #define LAS __attribute__((address_space(3)))
; __device__ __forceinline__ unsigned pk2(float lo, float hi) { const pkf2_t v = {lo, hi}; const pkb2_t b = __builtin_convertvector(v, pkb2_t); return __builtin_bit_cast(unsigned, b); }
; __device__ __forceinline__ f32x4 mma16(bf16x8 a, bf16x8 b, f32x4 c) { return __builtin_amdgcn_mfma_f32_16x16x32_bf16(a, b, c, 0, 0, 0); }
; __device__ __forceinline__ void hgrn_passA(Frame& F, u32x2v* HU, float* HD) {
;     ...
;             for (int jj = 0; jj < 4; ++jj) *(LAS v4u*)(KT + sw512b(8 * c8 + 4 * jh + jj, tq)) = (v4u){ke[jj][0], ke[jj][1], ke[jj][2], ke[jj][3]};
;             __builtin_amdgcn_sched_barrier(0);
;             if (jh == 0) {
; #pragma unroll
;                 for (int i = 0; i < 8; ++i) vq[i] = *(const GAS v4u*)(F.V + rbase + (size_t)i * 512);
;             }
;         }
; #pragma unroll
;         for (int j = 0; j < 8; ++j) {
;             unsigned vv[4];
; #pragma unroll
;             for (int p = 0; p < 4; ++p) { const unsigned lo = (j & 1) ? (vq[2 * p][j >> 1] >> 16) : (vq[2 * p][j >> 1] & 0xffffu), hi = (j & 1) ? (vq[2 * p + 1][j >> 1] & 0xffff0000u) : (vq[2 * p + 1][j >> 1] << 16); vv[p] = lo | hi; }
;             *(LAS v4u*)(VT + sw512b(8 * c8 + j, tq)) = (v4u){vv[0], vv[1], vv[2], vv[3]}; }
;         __syncthreads();
;         f32x4 acc[8];
; #pragma unroll
;         for (int n = 0; n < 8; ++n) acc[n] = (f32x4){0.f, 0.f, 0.f, 0.f};
; #pragma unroll
;         for (int ks = 0; ks < 8; ++ks) {
;             const bf16x8 af = ldfrag(KT + sw512b(16 * w + l15, 4 * ks + lq));
; #pragma unroll
;             for (int n = 0; n < 8; ++n) acc[n] = mma16(af, ldfrag(VT + sw512b(16 * n + l15, 4 * ks + lq)), acc[n]);
;         }
; #pragma unroll
;         for (int n = 0; n < 8; ++n) HU[(((size_t)u * 8 + w) * 8 + n) * 64 + lane] = (u32x2v){pk2(acc[n][0], acc[n][1]), pk2(acc[n][2], acc[n][3])};
	v_lshl_add_u32 v190, v60, 4, s2
	v_xor_b32_e32 v60, v46, v56
	v_lshrrev_b32_e32 v112, 4, v0
	v_xor_b32_e32 v7, v111, v0
	v_bitop3_b32 v10, v54, v0, 1 bitop3:0x36
	v_bitop3_b32 v13, v54, v0, 2 bitop3:0x36
	v_bitop3_b32 v16, v54, v0, 3 bitop3:0x36
	v_bitop3_b32 v19, v54, v0, 4 bitop3:0x36
	v_bitop3_b32 v22, v54, v0, 5 bitop3:0x36
	v_bitop3_b32 v25, v54, v0, 6 bitop3:0x36
	v_bitop3_b32 v28, v54, v0, 7 bitop3:0x36
	v_lshl_add_u32 v191, v60, 4, s2
	v_xor_b32_e32 v60, v49, v56
	v_xor_b32_e32 v56, v52, v56
	s_mov_b32 s1, 0
	s_lshl_b32 s0, s0, 3
	v_bitop3_b32 v7, v7, v112, 15 bitop3:0x6c
	v_bitop3_b32 v10, v10, v112, 15 bitop3:0x6c
	v_bitop3_b32 v13, v13, v112, 15 bitop3:0x6c
	v_bitop3_b32 v16, v16, v112, 15 bitop3:0x6c
	v_bitop3_b32 v19, v19, v112, 15 bitop3:0x6c
	v_bitop3_b32 v22, v22, v112, 15 bitop3:0x6c
	v_bitop3_b32 v25, v25, v112, 15 bitop3:0x6c
	v_bitop3_b32 v28, v28, v112, 15 bitop3:0x6c
	v_lshl_add_u32 v193, v56, 4, s2
	v_or_b32_e32 v56, 28, v55
	v_lshlrev_b32_e32 v7, 4, v7
	v_or_b32_e32 v9, 1, v54
	v_lshlrev_b32_e32 v10, 4, v10
	v_or_b32_e32 v12, 2, v54
	v_lshlrev_b32_e32 v13, 4, v13
	v_or_b32_e32 v15, 3, v54
	v_lshlrev_b32_e32 v16, 4, v16
	v_or_b32_e32 v18, 4, v54
	v_lshlrev_b32_e32 v19, 4, v19
	v_or_b32_e32 v21, 5, v54
	v_lshlrev_b32_e32 v22, 4, v22
	v_or_b32_e32 v24, 6, v54
	v_lshlrev_b32_e32 v25, 4, v25
	v_or_b32_e32 v27, 7, v54
	v_lshlrev_b32_e32 v28, 4, v28
	v_bitop3_b32 v32, v4, v55, 15 bitop3:0x6c
	v_xor_b32_e32 v33, v31, v55
	v_xor_b32_e32 v36, v34, v55
	v_xor_b32_e32 v39, v37, v55
	v_xor_b32_e32 v42, v40, v55
	v_xor_b32_e32 v45, v43, v55
	v_xor_b32_e32 v48, v46, v55
	v_xor_b32_e32 v51, v49, v55
	v_bitop3_b32 v4, v4, v56, 15 bitop3:0x6c
	v_xor_b32_e32 v31, v31, v56
	v_xor_b32_e32 v34, v34, v56
	v_xor_b32_e32 v37, v37, v56
	v_xor_b32_e32 v40, v40, v56
	v_xor_b32_e32 v43, v43, v56
	v_xor_b32_e32 v46, v46, v56
	v_xor_b32_e32 v49, v49, v56
	v_xor_b32_e32 v52, v52, v56
	s_lshl_b64 s[0:1], s[0:1], 9
	v_lshlrev_b32_e32 v6, 9, v54
	v_add_u32_e32 v8, 0, v7
	v_lshlrev_b32_e32 v9, 9, v9
	v_add_u32_e32 v11, 0, v10
	v_lshlrev_b32_e32 v12, 9, v12
	v_add_u32_e32 v14, 0, v13
	v_lshlrev_b32_e32 v15, 9, v15
	v_add_u32_e32 v17, 0, v16
	v_lshlrev_b32_e32 v18, 9, v18
	v_add_u32_e32 v20, 0, v19
	v_lshlrev_b32_e32 v21, 9, v21
	v_add_u32_e32 v23, 0, v22
	v_lshlrev_b32_e32 v24, 9, v24
	v_add_u32_e32 v26, 0, v25
	v_lshlrev_b32_e32 v27, 9, v27
	v_add_u32_e32 v29, 0, v28
	v_add_u32_e32 v7, s2, v7
	v_add_u32_e32 v10, s2, v10
	v_add_u32_e32 v13, s2, v13
	v_add_u32_e32 v16, s2, v16
	v_add_u32_e32 v19, s2, v19
	v_add_u32_e32 v22, s2, v22
	v_add_u32_e32 v25, s2, v25
	v_add_u32_e32 v28, s2, v28
	v_lshlrev_b32_e32 v30, 9, v110
	v_lshlrev_b32_e32 v32, 4, v32
	v_lshl_add_u32 v33, v33, 4, s2
	v_lshl_add_u32 v36, v36, 4, s2
	v_lshl_add_u32 v39, v39, 4, s2
	v_lshl_add_u32 v42, v42, 4, s2
	v_lshl_add_u32 v45, v45, 4, s2
	v_lshl_add_u32 v48, v48, 4, s2
	v_lshl_add_u32 v51, v51, 4, s2
	v_lshl_add_u32 v192, v60, 4, s2
	v_lshlrev_b32_e32 v4, 4, v4
	v_lshl_add_u32 v31, v31, 4, s2
	v_lshl_add_u32 v34, v34, 4, s2
	v_lshl_add_u32 v37, v37, 4, s2
	v_lshl_add_u32 v40, v40, 4, s2
	v_lshl_add_u32 v43, v43, 4, s2
	v_lshl_add_u32 v46, v46, 4, s2
	v_lshl_add_u32 v49, v49, 4, s2
	v_lshl_add_u32 v52, v52, 4, s2
	v_lshl_add_u64 v[2:3], v[2:3], 0, s[0:1]
	s_mov_b64 s[0:1], 0x4200000
	v_lshlrev_b32_e32 v113, 3, v112
	v_lshl_add_u32 v115, v112, 9, v114
	v_cmp_lt_u32_e32 vcc, 15, v0
	v_lshl_add_u64 v[60:61], v[2:3], 0, s[0:1]
	s_movk_i32 s2, 0x1000
	s_mov_b32 s3, 0xffff
	v_add_u32_e32 v56, v8, v6
	v_add_u32_e32 v116, v11, v9
	v_add_u32_e32 v117, v14, v12
	v_add_u32_e32 v118, v17, v15
	v_add_u32_e32 v119, v20, v18
	v_add_u32_e32 v120, v23, v21
	v_add_u32_e32 v121, v26, v24
	v_add_u32_e32 v122, v29, v27
	v_add_u32_e32 v123, v7, v6
	s_mov_b32 s8, 0xffff0000
	v_add_u32_e32 v124, v10, v9
	v_add_u32_e32 v125, v13, v12
	v_add_u32_e32 v126, v16, v15
	v_add_u32_e32 v127, v19, v18
	v_add_u32_e32 v128, v22, v21
	v_add_u32_e32 v129, v25, v24
	v_add_u32_e32 v130, v28, v27
	v_add_u32_e32 v131, v5, v32
	v_add_u32_e32 v132, v33, v30
	v_add_u32_e32 v133, v36, v35
	v_add_u32_e32 v134, v39, v38
	v_add_u32_e32 v135, v42, v41
	v_add_u32_e32 v136, v45, v44
	v_add_u32_e32 v137, v48, v47
	v_add_u32_e32 v138, v51, v50
	v_add_u32_e32 v139, v62, v53
	v_add_u32_e32 v140, v5, v63
	v_add_u32_e32 v141, v64, v30
	v_add_u32_e32 v142, v65, v35
	v_add_u32_e32 v143, v66, v38
	v_add_u32_e32 v144, v67, v41
	v_add_u32_e32 v145, v68, v44
	v_add_u32_e32 v146, v69, v47
	v_add_u32_e32 v147, v70, v50
	v_add_u32_e32 v148, v71, v53
	v_add_u32_e32 v149, v5, v72
	v_add_u32_e32 v150, v73, v30
	v_add_u32_e32 v151, v74, v35
	v_add_u32_e32 v152, v75, v38
	v_add_u32_e32 v153, v76, v41
	v_add_u32_e32 v154, v77, v44
	v_add_u32_e32 v155, v78, v47
	v_add_u32_e32 v156, v79, v50
	v_add_u32_e32 v157, v80, v53
	v_add_u32_e32 v158, v5, v81
	v_add_u32_e32 v159, v82, v30
	v_add_u32_e32 v160, v83, v35
	v_add_u32_e32 v161, v84, v38
	v_add_u32_e32 v162, v85, v41
	v_add_u32_e32 v163, v86, v44
	v_add_u32_e32 v164, v87, v47
	v_add_u32_e32 v165, v88, v50
	v_add_u32_e32 v166, v89, v53
	v_add_u32_e32 v167, v5, v90
	v_add_u32_e32 v168, v91, v30
	v_add_u32_e32 v169, v92, v35
	v_add_u32_e32 v170, v93, v38
	v_add_u32_e32 v171, v94, v41
	v_add_u32_e32 v172, v95, v44
	v_add_u32_e32 v173, v96, v47
	v_add_u32_e32 v174, v97, v50
	v_add_u32_e32 v175, v98, v53
	v_add_u32_e32 v176, v5, v99
	v_add_u32_e32 v177, v100, v30
	v_add_u32_e32 v178, v101, v35
	v_add_u32_e32 v179, v102, v38
	v_add_u32_e32 v180, v103, v41
	v_add_u32_e32 v181, v104, v44
	v_add_u32_e32 v182, v105, v47
	v_add_u32_e32 v183, v106, v50
	v_add_u32_e32 v184, v107, v53
	v_add_u32_e32 v185, v5, v108
	v_add_u32_e32 v186, v109, v30
	v_add_u32_e32 v187, v187, v35
	v_add_u32_e32 v188, v188, v38
	v_add_u32_e32 v189, v189, v41
	v_add_u32_e32 v190, v190, v44
	v_add_u32_e32 v191, v191, v47
	v_add_u32_e32 v192, v192, v50
	v_add_u32_e32 v193, v193, v53
	v_add_u32_e32 v194, v5, v4
	v_add_u32_e32 v195, v31, v30
	v_add_u32_e32 v196, v34, v35
	v_add_u32_e32 v197, v37, v38
	v_add_u32_e32 v198, v40, v41
	v_add_u32_e32 v199, v43, v44
	v_add_u32_e32 v200, v46, v47
	v_add_u32_e32 v201, v49, v50
	v_add_u32_e32 v203, v52, v53
	s_mov_b32 s4, s88
	s_branch .LBB0_569
